# code placement pin extended: .p2align 6 also on the attention, SGU MFMA, mixer extra-GEMM, pool-GEMM and final LayerNorm loop heads (on top of v39)
# baseline (speedup 1.0000x reference)
; #define LAS __attribute__((address_space(3)))
; __device__ __forceinline__ void attn_item(KP p, LAS unsigned char* lds, int l, int n, int hk) {
;     ...
;     __syncthreads();
;     const int h = hk * 8 + wid;
;     const float sink = p->in[8][l * 16 + h];
;     const LAS float* bh = bias + wid * 128;
;     float bv[9][4];
; #pragma unroll
;     for (int k9 = 0; k9 < 9; ++k9)
; #pragma unroll
;         for (int j = 0; j < 4; ++j) { const int dist = 128 - 16 * k9 + fr - fq * 4 - j; bv[k9][j] = (dist >= 0 && dist < 128) ? bh[dist & 127] : -1e30f; }
;     bf16x8 qnA0, qnA1, qnB0, qnB1;
;     { const bf16_t* qrow = HM + (size_t)(n * 128 + fr) * HMW + C_Q + h * 64 + fq * 8; qnA0 = *(const bf16x8*)qrow; qnA1 = *(const bf16x8*)(qrow + 32);
;       qnB0 = *(const bf16x8*)(qrow + (size_t)16 * HMW); qnB1 = *(const bf16x8*)(qrow + (size_t)16 * HMW + 32); }
; #pragma unroll 1
;     for (int t2 = 0; t2 < 4; ++t2) {
;         const int qa = 2 * t2; const int tokA = n * 128 + qa * 16 + fr, tokB = tokA + 16;
;         const bf16x8 qA0 = qnA0, qA1 = qnA1, qB0 = qnB0, qB1 = qnB1;
;         { const int tn = n * 128 + (t2 < 3 ? qa + 2 : qa) * 16 + fr; const bf16_t* qrow = HM + (size_t)tn * HMW + C_Q + h * 64 + fq * 8;
;           qnA0 = *(const bf16x8*)qrow; qnA1 = *(const bf16x8*)(qrow + 32); qnB0 = *(const bf16x8*)(qrow + (size_t)16 * HMW); qnB1 = *(const bf16x8*)(qrow + (size_t)16 * HMW + 32); }
.LBB0_497:
	s_or_b64 exec, exec, s[40:41]
	s_waitcnt lgkmcnt(0)
	s_barrier
	s_load_dwordx2 s[40:41], s[0:1], 0x40
	s_ashr_i32 s6, s62, 6
	v_add_u32_e32 v5, s6, v0
	v_readlane_b32 s42, v240, 38
	v_and_b32_e32 v4, 15, v10
	v_bfe_u32 v3, v10, 4, 2
	v_add_u32_e32 v6, s42, v5
	v_ashrrev_i32_e32 v7, 31, v6
	s_waitcnt lgkmcnt(0)
	v_lshl_add_u64 v[6:7], v[6:7], 2, s[40:41]
	global_load_dword v124, v[6:7], off
	s_lshl_b32 s6, s6, 9
	s_add_i32 s6, s6, 0
	v_or_b32_e32 v0, 0x80, v4
	v_lshlrev_b32_e32 v2, 2, v3
	s_add_i32 s6, s6, 0x11c00
	v_sub_u32_e32 v6, v0, v2
	s_movk_i32 s44, 0x80
	v_sub_u32_e32 v7, v4, v2
	v_cmp_gt_u32_e32 vcc, s44, v6
	v_mov_b32_e32 v125, 0xf149f2ca
	v_lshl_add_u32 v6, v7, 2, s6
	v_mov_b32_e32 v126, 0xf149f2ca
	s_and_saveexec_b64 s[40:41], vcc
	ds_read_b32 v126, v6 offset:512
	s_or_b64 exec, exec, s[40:41]
	v_not_b32_e32 v8, v2
	v_add_u32_e32 v9, v0, v8
	v_cmp_gt_u32_e32 vcc, s44, v9
	s_and_saveexec_b64 s[40:41], vcc
	v_add_u32_e32 v8, v4, v8
	v_lshl_add_u32 v8, v8, 2, s6
	ds_read_b32 v125, v8 offset:512
	s_or_b64 exec, exec, s[40:41]
	v_or_b32_e32 v8, 2, v2
	v_sub_u32_e32 v9, v0, v8
	v_cmp_gt_u32_e32 vcc, s44, v9
	v_mov_b32_e32 v127, 0xf149f2ca
	v_mov_b32_e32 v128, 0xf149f2ca
	s_and_saveexec_b64 s[40:41], vcc
	v_sub_u32_e32 v8, v4, v8
	v_lshl_add_u32 v8, v8, 2, s6
	ds_read_b32 v128, v8 offset:512
	s_or_b64 exec, exec, s[40:41]
	v_or_b32_e32 v8, 3, v2
	v_sub_u32_e32 v9, v0, v8
	v_cmp_gt_u32_e32 vcc, s44, v9
	s_and_saveexec_b64 s[40:41], vcc
	v_sub_u32_e32 v8, v4, v8
	v_lshl_add_u32 v8, v8, 2, s6
	ds_read_b32 v127, v8 offset:512
	s_or_b64 exec, exec, s[40:41]
	ds_read2_b32 v[68:69], v6 offset0:111 offset1:112
	ds_read2_b32 v[70:71], v6 offset0:109 offset1:110
	ds_read2_b32 v[72:73], v6 offset0:95 offset1:96
	ds_read2_b32 v[74:75], v6 offset0:93 offset1:94
	ds_read2_b32 v[76:77], v6 offset0:79 offset1:80
	ds_read2_b32 v[78:79], v6 offset0:77 offset1:78
	ds_read2_b32 v[80:81], v6 offset0:63 offset1:64
	ds_read2_b32 v[82:83], v6 offset0:61 offset1:62
	ds_read2_b32 v[84:85], v6 offset0:47 offset1:48
	ds_read2_b32 v[86:87], v6 offset0:45 offset1:46
	ds_read2_b32 v[88:89], v6 offset0:31 offset1:32
	ds_read2_b32 v[90:91], v6 offset0:29 offset1:30
	ds_read2_b32 v[92:93], v6 offset0:15 offset1:16
	ds_read2_b32 v[94:95], v6 offset0:13 offset1:14
	v_cmp_gt_u32_e32 vcc, s44, v7
	v_mov_b32_e32 v130, 0xf149f2ca
	v_mov_b32_e32 v129, 0xf149f2ca
	s_and_saveexec_b64 s[40:41], vcc
	ds_read_b32 v129, v6
	s_or_b64 exec, exec, s[40:41]
	v_or_b32_e32 v6, 0x81, v2
	v_sub_u32_e32 v7, v0, v6
	v_cmp_gt_u32_e32 vcc, s44, v7
	s_and_saveexec_b64 s[40:41], vcc
	v_sub_u32_e32 v6, v4, v6
	v_lshl_add_u32 v6, v6, 2, s6
	ds_read_b32 v130, v6 offset:512
	s_or_b64 exec, exec, s[40:41]
	v_or_b32_e32 v6, 0x82, v2
	v_sub_u32_e32 v7, v0, v6
	v_cmp_gt_u32_e32 vcc, s44, v7
	v_mov_b32_e32 v131, 0xf149f2ca
	v_mov_b32_e32 v132, 0xf149f2ca
	s_and_saveexec_b64 s[40:41], vcc
	v_sub_u32_e32 v6, v4, v6
	v_lshl_add_u32 v6, v6, 2, s6
	ds_read_b32 v132, v6 offset:512
	s_or_b64 exec, exec, s[40:41]
	v_or_b32_e32 v6, 0x83, v2
	v_sub_u32_e32 v0, v0, v6
	v_cmp_gt_u32_e32 vcc, s44, v0
	s_and_saveexec_b64 s[40:41], vcc
	v_sub_u32_e32 v0, v4, v6
	v_lshl_add_u32 v0, v0, 2, s6
	ds_read_b32 v131, v0 offset:512
	s_or_b64 exec, exec, s[40:41]
	v_or_b32_e32 v133, s61, v4
	v_mul_lo_u32 v0, v133, s55
	v_lshlrev_b32_e32 v8, 6, v5
	v_lshl_add_u64 v[6:7], v[0:1], 1, s[36:37]
	v_ashrrev_i32_e32 v9, 31, v8
	v_lshl_add_u64 v[6:7], v[8:9], 1, v[6:7]
	v_lshlrev_b32_e32 v0, 4, v3
	v_lshl_add_u64 v[6:7], v[6:7], 0, v[0:1]
	v_add_co_u32_e32 v12, vcc, s33, v6
	v_lshl_add_u64 v[10:11], v[6:7], 0, s[16:17]
	s_nop 0
	v_addc_co_u32_e32 v13, vcc, 0, v7, vcc
	v_add_co_u32_e32 v6, vcc, s59, v6
	global_load_dwordx4 v[20:23], v[12:13], off
	global_load_dwordx4 v[32:35], v[10:11], off offset:64
	v_addc_co_u32_e32 v7, vcc, 0, v7, vcc
	global_load_dwordx4 v[24:27], v[6:7], off
	global_load_dwordx4 v[28:31], v[6:7], off offset:64
	v_and_b32_e32 v5, 64, v172
	v_lshlrev_b32_e32 v6, 3, v3
	v_xor_b32_e32 v3, 16, v172
	v_add_u32_e32 v5, 64, v5
	v_cmp_lt_i32_e32 vcc, v3, v5
	s_cmp_lt_u32 s25, 2
	s_cselect_b64 s[40:41], -1, 0
	v_cndmask_b32_e32 v3, v172, v3, vcc
	v_lshlrev_b32_e32 v134, 2, v3
	v_xor_b32_e32 v3, 32, v172
	v_cmp_lt_i32_e32 vcc, v3, v5
	s_add_i32 s6, 0, 0x9000
	v_or_b32_e32 v10, v8, v2
	v_cndmask_b32_e32 v3, v172, v3, vcc
	v_lshlrev_b32_e32 v135, 2, v3
	v_mul_u32_u24_e32 v3, 0x230, v4
	v_add3_u32 v99, v3, v6, s6
	v_mul_u32_u24_e32 v3, 0x90, v4
	v_add3_u32 v3, v3, v0, 0
	s_lshr_b32 s6, s24, 7
	v_lshlrev_b32_e32 v0, 10, v4
	v_readlane_b32 s42, v240, 36
	v_lshl_or_b32 v98, s6, 17, v0
	s_mul_i32 s6, s6, 0x108000
	v_ashrrev_i32_e32 v11, 31, v10
	v_readlane_b32 s43, v240, 37
	v_mov_b32_e32 v0, s6
	s_mov_b32 s61, 0
	v_lshl_add_u64 v[96:97], v[10:11], 1, s[42:43]
	v_mad_u32_u24 v100, v4, s55, v0
	v_lshlrev_b64 v[102:103], 1, v[8:9]
	v_lshlrev_b32_e32 v104, 1, v6
	v_lshlrev_b32_e32 v106, 1, v2
	s_mov_b32 s6, 0
	.p2align 6

; __device__ __forceinline__ float bflo(unsigned w) { return __uint_as_float(w << 16); }
; __device__ __forceinline__ float bfhi(unsigned w) { return __uint_as_float(w & 0xffff0000u); }
; __device__ __forceinline__ void sgu_item(KP p, LAS unsigned char* lds, int l, int n) {
;     ...
;         for (int tti = 0; tti < 4; ++tti) {
;     ...
; #pragma unroll
;             for (int dt = 0; dt < 8; ++dt) { const int col = h * 128 + dt * 16 + fq * 4;
;                 u32x2 w; w.x = pk2((acc[dt][0] + bs) * bflo(uu[dt].x), (acc[dt][1] + bs) * bfhi(uu[dt].x));
;                 w.y = pk2((acc[dt][2] + bs) * bflo(uu[dt].y), (acc[dt][3] + bs) * bfhi(uu[dt].y));
;                 *(u32x2*)(YB + tok * 1024 + col) = w; }
;         }
.LBB0_527:
	s_waitcnt vmcnt(0)
	v_pk_add_f32 v[62:63], v[116:117], v[62:63] op_sel_hi:[0,1]
	v_lshlrev_b32_e32 v68, 16, v130
	v_and_b32_e32 v69, 0xffff0000, v130
	v_pk_mul_f32 v[62:63], v[62:63], v[68:69]
	v_pk_add_f32 v[64:65], v[116:117], v[64:65] op_sel_hi:[0,1]
	v_lshlrev_b32_e32 v68, 16, v131
	v_and_b32_e32 v69, 0xffff0000, v131
	v_lshlrev_b64 v[66:67], 11, v[0:1]
	v_pk_mul_f32 v[64:65], v[64:65], v[68:69]
	v_cvt_pk_bf16_f32 v62, v62, v63
	v_cvt_pk_bf16_f32 v63, v64, v65
	v_lshl_add_u64 v[64:65], v[110:111], 0, v[66:67]
	global_store_dwordx2 v[64:65], v[62:63], off
	v_pk_add_f32 v[58:59], v[116:117], v[58:59] op_sel_hi:[0,1]
	v_lshlrev_b32_e32 v62, 16, v128
	v_and_b32_e32 v63, 0xffff0000, v128
	v_pk_mul_f32 v[58:59], v[58:59], v[62:63]
	v_pk_add_f32 v[60:61], v[116:117], v[60:61] op_sel_hi:[0,1]
	v_lshlrev_b32_e32 v62, 16, v129
	v_and_b32_e32 v63, 0xffff0000, v129
	v_pk_mul_f32 v[60:61], v[60:61], v[62:63]
	v_cvt_pk_bf16_f32 v58, v58, v59
	v_cvt_pk_bf16_f32 v59, v60, v61
	global_store_dwordx2 v[64:65], v[58:59], off offset:32
	v_pk_add_f32 v[54:55], v[116:117], v[54:55] op_sel_hi:[0,1]
	v_lshlrev_b32_e32 v58, 16, v126
	v_and_b32_e32 v59, 0xffff0000, v126
	v_pk_mul_f32 v[54:55], v[54:55], v[58:59]
	v_pk_add_f32 v[56:57], v[116:117], v[56:57] op_sel_hi:[0,1]
	v_lshlrev_b32_e32 v58, 16, v127
	v_and_b32_e32 v59, 0xffff0000, v127
	v_pk_mul_f32 v[56:57], v[56:57], v[58:59]
	v_cvt_pk_bf16_f32 v54, v54, v55
	v_cvt_pk_bf16_f32 v55, v56, v57
	global_store_dwordx2 v[64:65], v[54:55], off offset:64
	v_pk_add_f32 v[50:51], v[116:117], v[50:51] op_sel_hi:[0,1]
	v_lshlrev_b32_e32 v54, 16, v124
	v_and_b32_e32 v55, 0xffff0000, v124
	v_pk_mul_f32 v[50:51], v[50:51], v[54:55]
	v_pk_add_f32 v[52:53], v[116:117], v[52:53] op_sel_hi:[0,1]
	v_lshlrev_b32_e32 v54, 16, v125
	v_and_b32_e32 v55, 0xffff0000, v125
	v_pk_mul_f32 v[52:53], v[52:53], v[54:55]
	v_cvt_pk_bf16_f32 v50, v50, v51
	v_cvt_pk_bf16_f32 v51, v52, v53
	global_store_dwordx2 v[64:65], v[50:51], off offset:96
	v_pk_add_f32 v[46:47], v[116:117], v[46:47] op_sel_hi:[0,1]
	v_lshlrev_b32_e32 v50, 16, v122
	v_and_b32_e32 v51, 0xffff0000, v122
	v_pk_mul_f32 v[46:47], v[46:47], v[50:51]
	v_pk_add_f32 v[48:49], v[116:117], v[48:49] op_sel_hi:[0,1]
	v_lshlrev_b32_e32 v50, 16, v123
	v_and_b32_e32 v51, 0xffff0000, v123
	v_pk_mul_f32 v[48:49], v[48:49], v[50:51]
	v_cvt_pk_bf16_f32 v46, v46, v47
	v_cvt_pk_bf16_f32 v47, v48, v49
	global_store_dwordx2 v[64:65], v[46:47], off offset:128
	v_pk_add_f32 v[42:43], v[116:117], v[42:43] op_sel_hi:[0,1]
	v_lshlrev_b32_e32 v46, 16, v120
	v_and_b32_e32 v47, 0xffff0000, v120
	v_pk_mul_f32 v[42:43], v[42:43], v[46:47]
	v_pk_add_f32 v[44:45], v[116:117], v[44:45] op_sel_hi:[0,1]
	v_lshlrev_b32_e32 v46, 16, v121
	v_and_b32_e32 v47, 0xffff0000, v121
	v_pk_mul_f32 v[44:45], v[44:45], v[46:47]
	v_cvt_pk_bf16_f32 v42, v42, v43
	v_cvt_pk_bf16_f32 v43, v44, v45
	global_store_dwordx2 v[64:65], v[42:43], off offset:160
	v_pk_add_f32 v[38:39], v[116:117], v[38:39] op_sel_hi:[0,1]
	v_lshlrev_b32_e32 v42, 16, v118
	v_and_b32_e32 v43, 0xffff0000, v118
	v_pk_mul_f32 v[38:39], v[38:39], v[42:43]
	v_pk_add_f32 v[40:41], v[116:117], v[40:41] op_sel_hi:[0,1]
	v_lshlrev_b32_e32 v42, 16, v119
	v_and_b32_e32 v43, 0xffff0000, v119
	v_pk_mul_f32 v[40:41], v[40:41], v[42:43]
	v_cvt_pk_bf16_f32 v38, v38, v39
	v_cvt_pk_bf16_f32 v39, v40, v41
	global_store_dwordx2 v[64:65], v[38:39], off offset:192
	v_pk_add_f32 v[34:35], v[116:117], v[34:35] op_sel_hi:[0,1]
	v_lshlrev_b32_e32 v38, 16, v114
	v_and_b32_e32 v39, 0xffff0000, v114
	v_pk_mul_f32 v[34:35], v[34:35], v[38:39]
	v_pk_add_f32 v[36:37], v[116:117], v[36:37] op_sel_hi:[0,1]
	v_lshlrev_b32_e32 v38, 16, v115
	v_and_b32_e32 v39, 0xffff0000, v115
	s_add_u32 s44, s44, 0x2000
	v_pk_mul_f32 v[36:37], v[36:37], v[38:39]
	s_addc_u32 s45, s45, 0
	s_add_i32 s24, s24, 1
	v_cvt_pk_bf16_f32 v34, v34, v35
	v_cvt_pk_bf16_f32 v35, v36, v37
	s_cmpk_eq_u32 s44, 0x8000
	v_add_u32_e32 v180, 16, v180
	global_store_dwordx2 v[64:65], v[34:35], off offset:224
	s_cbranch_scc1 .LBB0_523
	.p2align 6

; #define PG8_STAGE(bufoff, gbase, voff) do { _Pragma("unroll") for (int _i = 0; _i < 2; ++_i) \
;         __builtin_amdgcn_global_load_lds((const unsigned*)((const char*)(gbase) + (voff)[_i]), (LAS unsigned*)(lds + (bufoff) + ldsw + _i * 8192), 16, 0, 0); } while (0)
; #define PG8_WAIT_V(n) asm volatile("s_waitcnt vmcnt(" #n ")" ::: "memory")
; #define PG8_BAR __builtin_amdgcn_s_barrier()
; template <bool ALIGN_EPI, bool SP2, class Epi, class Sched>
; __device__ __forceinline__ void gemm_phase(LAS unsigned char* lds, const Gemm g, const Sched& S, const Epi& E) {
;     ...
;     f32x4 acc[2][2][4][2];
; #pragma unroll
;     for (int a = 0; a < 2; ++a)
; #pragma unroll
;         for (int b = 0; b < 2; ++b)
; #pragma unroll
;             for (int m = 0; m < 4; ++m)
; #pragma unroll
;                 for (int n = 0; n < 2; ++n) acc[a][b][m][n] = (f32x4){0.f, 0.f, 0.f, 0.f};
;     bf16x8 At[4][2], B0[2][2], B1[2][2];
;     const char* cA = (const char*)g.A + (size_t)cur.pm * tstep; const char* cB = (const char*)g.Bt + (size_t)cur.pn * tstep;
;     if constexpr (SP2) {
;         PG8_STAGE(PG8_SB(0, 0), cB, voffB); PG8_STAGE(PG8_SB(0, 1), cB + hstep, voffB); PG8_STAGE(PG8_SA(0, 0), cA, voffA); PG8_STAGE(PG8_SA(0, 1), cA + hstep, voffA);
;         if (wr == 1) PG8_BAR;
;         PG8_WAIT_V(2); PG8_BAR;
;         PG8_STAGE(PG8_SB(1, 0), cB + kstep, voffB); PG8_STAGE(PG8_SA(1, 0), cA + kstep, voffA); PG8_STAGE(PG8_SB(1, 1), cB + hstep + kstep, voffB);
;         PG8_WAIT_V(6); PG8_BAR;
;     } else {
;         PG8_STAGE(PG8_SB(0, 0), cB, voffB); PG8_STAGE(PG8_SA(0, 0), cA, voffA); PG8_STAGE(PG8_SB(0, 1), cB + hstep, voffB); PG8_STAGE(PG8_SA(0, 1), cA + hstep, voffA);
;         if (wr == 1) PG8_BAR;
;         PG8_WAIT_V(4); PG8_BAR;
;         PG8_STAGE(PG8_SB(1, 0), cB + kstep, voffB); PG8_STAGE(PG8_SA(1, 0), cA + kstep, voffA); PG8_STAGE(PG8_SB(1, 1), cB + hstep + kstep, voffB);
;         PG8_WAIT_V(6); PG8_BAR;
;     }
.LBB0_544:
	v_lshl_add_u64 v[4:5], s[40:41], 0, v[0:1]
	v_mov_b32_e32 v135, v1
	v_lshl_add_u64 v[6:7], s[40:41], 0, v[134:135]
	v_mov_b32_e32 v131, v1
	v_bfe_u32 v148, v2, 4, 2
	v_and_b32_e32 v150, 15, v2
	s_add_i32 m0, s62, 0x18000
	v_lshl_add_u64 v[2:3], v[4:5], 0, s[8:9]
	v_lshl_add_u64 v[12:13], s[44:45], 0, v[130:131]
	v_mov_b32_e32 v133, v1
	s_waitcnt vmcnt(2)
	s_barrier
	global_load_lds_dwordx4 v[2:3], off
	v_lshl_add_u64 v[2:3], v[6:7], 0, s[8:9]
	s_add_i32 m0, s62, 0x1a000
	s_add_i32 s66, s62, 0x8000
	v_lshl_add_u64 v[14:15], s[44:45], 0, v[132:133]
	global_load_lds_dwordx4 v[2:3], off
	v_lshl_add_u64 v[2:3], v[12:13], 0, s[8:9]
	s_mov_b32 m0, s66
	s_add_i32 s67, s62, 0xa000
	v_lshl_add_u64 v[8:9], s[96:97], 0, v[0:1]
	global_load_lds_dwordx4 v[2:3], off
	v_lshl_add_u64 v[2:3], v[14:15], 0, s[8:9]
	s_mov_b32 m0, s67
	v_lshl_add_u64 v[10:11], s[96:97], 0, v[134:135]
	global_load_lds_dwordx4 v[2:3], off
	s_add_i32 m0, s62, 0x1c000
	v_lshl_add_u64 v[2:3], v[8:9], 0, s[8:9]
	global_load_lds_dwordx4 v[2:3], off
	v_lshl_add_u64 v[2:3], v[10:11], 0, s[8:9]
	s_add_i32 m0, s62, 0x1e000
	s_and_b32 s25, s24, 3
	global_load_lds_dwordx4 v[2:3], off
	s_waitcnt vmcnt(6)
	v_mov_b32_e32 v117, 0
	v_lshl_or_b32 v149, s69, 6, v150
	s_cmp_lt_i32 s46, 64
	v_mov_b32_e32 v116, v117
	v_mov_b32_e32 v115, v117
	v_mov_b32_e32 v114, v117
	v_mov_b32_e32 v129, v117
	v_mov_b32_e32 v128, v117
	v_mov_b32_e32 v127, v117
	v_mov_b32_e32 v126, v117
	v_mov_b32_e32 v101, v117
	v_mov_b32_e32 v100, v117
	v_mov_b32_e32 v99, v117
	v_mov_b32_e32 v98, v117
	v_mov_b32_e32 v113, v117
	v_mov_b32_e32 v112, v117
	v_mov_b32_e32 v111, v117
	v_mov_b32_e32 v110, v117
	v_mov_b32_e32 v85, v117
	v_mov_b32_e32 v84, v117
	v_mov_b32_e32 v83, v117
	v_mov_b32_e32 v82, v117
	v_mov_b32_e32 v97, v117
	v_mov_b32_e32 v96, v117
	v_mov_b32_e32 v95, v117
	v_mov_b32_e32 v94, v117
	v_mov_b32_e32 v69, v117
	v_mov_b32_e32 v68, v117
	v_mov_b32_e32 v67, v117
	v_mov_b32_e32 v66, v117
	v_mov_b32_e32 v81, v117
	v_mov_b32_e32 v80, v117
	v_mov_b32_e32 v79, v117
	v_mov_b32_e32 v78, v117
	v_mov_b32_e32 v125, v117
	v_mov_b32_e32 v124, v117
	v_mov_b32_e32 v123, v117
	v_mov_b32_e32 v122, v117
	v_mov_b32_e32 v121, v117
	v_mov_b32_e32 v120, v117
	v_mov_b32_e32 v119, v117
	v_mov_b32_e32 v118, v117
	v_mov_b32_e32 v109, v117
	v_mov_b32_e32 v108, v117
	v_mov_b32_e32 v107, v117
	v_mov_b32_e32 v106, v117
	v_mov_b32_e32 v105, v117
	v_mov_b32_e32 v104, v117
	v_mov_b32_e32 v103, v117
	v_mov_b32_e32 v102, v117
	v_mov_b32_e32 v93, v117
	v_mov_b32_e32 v92, v117
	v_mov_b32_e32 v91, v117
	v_mov_b32_e32 v90, v117
	v_mov_b32_e32 v89, v117
	v_mov_b32_e32 v88, v117
	v_mov_b32_e32 v87, v117
	v_mov_b32_e32 v86, v117
	v_mov_b32_e32 v77, v117
	v_mov_b32_e32 v76, v117
	v_mov_b32_e32 v75, v117
	v_mov_b32_e32 v74, v117
	v_mov_b32_e32 v73, v117
	v_mov_b32_e32 v72, v117
	v_mov_b32_e32 v71, v117
	v_mov_b32_e32 v70, v117
	v_mov_b32_e32 v53, v117
	v_mov_b32_e32 v52, v117
	v_mov_b32_e32 v51, v117
	v_mov_b32_e32 v50, v117
	v_mov_b32_e32 v65, v117
	v_mov_b32_e32 v64, v117
	v_mov_b32_e32 v63, v117
	v_mov_b32_e32 v62, v117
	v_mov_b32_e32 v37, v117
	v_mov_b32_e32 v36, v117
	v_mov_b32_e32 v35, v117
	v_mov_b32_e32 v34, v117
	v_mov_b32_e32 v49, v117
	v_mov_b32_e32 v48, v117
	v_mov_b32_e32 v47, v117
	v_mov_b32_e32 v46, v117
	v_mov_b32_e32 v21, v117
	v_mov_b32_e32 v20, v117
	v_mov_b32_e32 v19, v117
	v_mov_b32_e32 v18, v117
	v_mov_b32_e32 v33, v117
	v_mov_b32_e32 v32, v117
	v_mov_b32_e32 v31, v117
	v_mov_b32_e32 v30, v117
	v_mov_b32_e32 v5, v117
	v_mov_b32_e32 v4, v117
	v_mov_b32_e32 v3, v117
	v_mov_b32_e32 v2, v117
	v_mov_b32_e32 v17, v117
	v_mov_b32_e32 v16, v117
	v_mov_b32_e32 v15, v117
	v_mov_b32_e32 v14, v117
	v_mov_b32_e32 v61, v117
	v_mov_b32_e32 v60, v117
	v_mov_b32_e32 v59, v117
	v_mov_b32_e32 v58, v117
	v_mov_b32_e32 v57, v117
	v_mov_b32_e32 v56, v117
	v_mov_b32_e32 v55, v117
	v_mov_b32_e32 v54, v117
	v_mov_b32_e32 v45, v117
	v_mov_b32_e32 v44, v117
	v_mov_b32_e32 v43, v117
	v_mov_b32_e32 v42, v117
	v_mov_b32_e32 v41, v117
	v_mov_b32_e32 v40, v117
	v_mov_b32_e32 v39, v117
	v_mov_b32_e32 v38, v117
	v_mov_b32_e32 v29, v117
	v_mov_b32_e32 v28, v117
	v_mov_b32_e32 v27, v117
	v_mov_b32_e32 v26, v117
	v_mov_b32_e32 v25, v117
	v_mov_b32_e32 v24, v117
	v_mov_b32_e32 v23, v117
	v_mov_b32_e32 v22, v117
	v_mov_b32_e32 v13, v117
	v_mov_b32_e32 v12, v117
	v_mov_b32_e32 v11, v117
	v_mov_b32_e32 v10, v117
	v_mov_b32_e32 v9, v117
	v_mov_b32_e32 v8, v117
	v_mov_b32_e32 v7, v117
	v_mov_b32_e32 v6, v117
	s_barrier
; #define PG8_WAIT_V(n) asm volatile("s_waitcnt vmcnt(" #n ")" ::: "memory")
; template <bool ALIGN_EPI, bool SP2, class Epi, class Sched>
; __device__ __forceinline__ void gemm_phase(LAS unsigned char* lds, const Gemm g, const Sched& S, const Epi& E) {
;     ...
;     const int aoff = lds_byte(wr * 64 + fr, fq * 8), boff = lds_byte(wc * 32 + fr, fq * 8);
;     ...
;     Unit cur, nxt; int ui = 0;
;     if (!S.next(0, cur)) return;
;     f32x4 acc[2][2][4][2];
; #pragma unroll
;     for (int a = 0; a < 2; ++a)
; #pragma unroll
;         for (int b = 0; b < 2; ++b)
; #pragma unroll
;             for (int m = 0; m < 4; ++m)
; #pragma unroll
;                 for (int n = 0; n < 2; ++n) acc[a][b][m][n] = (f32x4){0.f, 0.f, 0.f, 0.f};
;     bf16x8 At[4][2], B0[2][2], B1[2][2];
;     const char* cA = (const char*)g.A + (size_t)cur.pm * tstep; const char* cB = (const char*)g.Bt + (size_t)cur.pn * tstep;
;     if constexpr (SP2) {
;         PG8_STAGE(PG8_SB(0, 0), cB, voffB); PG8_STAGE(PG8_SB(0, 1), cB + hstep, voffB); PG8_STAGE(PG8_SA(0, 0), cA, voffA); PG8_STAGE(PG8_SA(0, 1), cA + hstep, voffA);
;         if (wr == 1) PG8_BAR;
;         PG8_WAIT_V(2); PG8_BAR;
;         PG8_STAGE(PG8_SB(1, 0), cB + kstep, voffB); PG8_STAGE(PG8_SA(1, 0), cA + kstep, voffA); PG8_STAGE(PG8_SB(1, 1), cB + hstep + kstep, voffB);
;         PG8_WAIT_V(6); PG8_BAR;
;     } else {
;         PG8_STAGE(PG8_SB(0, 0), cB, voffB); PG8_STAGE(PG8_SA(0, 0), cA, voffA); PG8_STAGE(PG8_SB(0, 1), cB + hstep, voffB); PG8_STAGE(PG8_SA(0, 1), cA + hstep, voffA);
;         if (wr == 1) PG8_BAR;
;         PG8_WAIT_V(4); PG8_BAR;
;         PG8_STAGE(PG8_SB(1, 0), cB + kstep, voffB); PG8_STAGE(PG8_SA(1, 0), cA + kstep, voffA); PG8_STAGE(PG8_SB(1, 1), cB + hstep + kstep, voffB);
;         PG8_WAIT_V(6); PG8_BAR;
;     }
;     for (;;) {
;         const bool has_next = S.next(ui + 1, nxt);
;         const char* nA = has_next ? (const char*)g.A + (size_t)nxt.pm * tstep : cA; const char* nB = has_next ? (const char*)g.Bt + (size_t)nxt.pn * tstep : cB;
;         for (int t = 0; t < nt; t += 2) {
;             const bool last = (t == nt - 2);
;             const char* a1 = cA + (size_t)(t + 1) * kstep;
;             const char* a2 = last ? nA : cA + (size_t)(t + 2) * kstep; const char* b2 = last ? nB : cB + (size_t)(t + 2) * kstep;
;             const char* a3 = a2 + kstep; const char* b3 = b2 + kstep;
	s_cbranch_scc1 .LBB0_547
	s_lshr_b32 s24, s47, 26
	v_lshlrev_b32_e32 v2, 6, v149
	v_lshlrev_b32_e32 v3, 4, v148
	s_movk_i32 s70, 0x3c0
	v_lshlrev_b32_e32 v4, 2, v149
	s_add_i32 s24, s46, s24
	v_and_or_b32 v2, v2, s70, v3
	s_lshl_b32 s69, s69, 13
	v_and_b32_e32 v4, 32, v4
	s_ashr_i32 s24, s24, 6
	v_bitop3_b32 v4, v2, s69, v4 bitop3:0xde
	v_lshl_or_b32 v2, v150, 6, v3
	v_lshlrev_b32_e32 v3, 2, v150
	s_add_i32 s68, s24, -2
	v_and_b32_e32 v3, 32, v3
	s_lshl_b32 s69, s25, 12
	v_bitop3_b32 v150, v2, s69, v3 bitop3:0xde
	s_add_u32 s69, s88, 0x100
	s_addc_u32 s70, s89, 0
	s_mul_i32 s47, s69, s47
	s_mul_hi_u32 s71, s69, s46
	s_add_i32 s47, s71, s47
	s_mul_i32 s70, s70, s46
	s_add_i32 s47, s47, s70
	s_mul_i32 s69, s69, s46
	v_add_u32_e32 v2, v152, v136
	s_add_u32 s46, s28, s69
	v_add_lshl_u32 v2, v2, v137, 1
	v_mov_b32_e32 v3, v1
	s_addc_u32 s47, s29, s47
	v_lshl_add_u64 v[136:137], s[46:47], 0, v[2:3]
	v_add_u32_e32 v2, v151, v138
	v_add_lshl_u32 v2, v2, v139, 1
	v_mov_b32_e32 v6, 0
	v_lshl_add_u64 v[138:139], s[46:47], 0, v[2:3]
	s_mov_b32 s69, 0
	s_mov_b64 s[46:47], 0xc300080
	v_add_u32_e32 v151, 0, v4
	v_mov_b32_e32 v7, v6
	v_mov_b32_e32 v8, v6
	v_mov_b32_e32 v9, v6
	v_mov_b32_e32 v10, v6
	v_mov_b32_e32 v11, v6
	v_mov_b32_e32 v12, v6
	v_mov_b32_e32 v13, v6
	v_mov_b32_e32 v22, v6
	v_mov_b32_e32 v23, v6
	v_mov_b32_e32 v24, v6
	v_mov_b32_e32 v25, v6
	v_mov_b32_e32 v26, v6
	v_mov_b32_e32 v27, v6
	v_mov_b32_e32 v28, v6
	v_mov_b32_e32 v29, v6
	v_mov_b32_e32 v38, v6
	v_mov_b32_e32 v39, v6
	v_mov_b32_e32 v40, v6
	v_mov_b32_e32 v41, v6
	v_mov_b32_e32 v42, v6
	v_mov_b32_e32 v43, v6
	v_mov_b32_e32 v44, v6
	v_mov_b32_e32 v45, v6
	v_mov_b32_e32 v54, v6
	v_mov_b32_e32 v55, v6
	v_mov_b32_e32 v56, v6
	v_mov_b32_e32 v57, v6
	v_mov_b32_e32 v58, v6
	v_mov_b32_e32 v59, v6
	v_mov_b32_e32 v60, v6
	v_mov_b32_e32 v61, v6
	v_mov_b32_e32 v14, v6
	v_mov_b32_e32 v15, v6
	v_mov_b32_e32 v16, v6
	v_mov_b32_e32 v17, v6
	v_mov_b32_e32 v2, v6
	v_mov_b32_e32 v3, v6
	v_mov_b32_e32 v4, v6
	v_mov_b32_e32 v5, v6
	v_mov_b32_e32 v30, v6
	v_mov_b32_e32 v31, v6
	v_mov_b32_e32 v32, v6
	v_mov_b32_e32 v33, v6
	v_mov_b32_e32 v18, v6
	v_mov_b32_e32 v19, v6
	v_mov_b32_e32 v20, v6
	v_mov_b32_e32 v21, v6
	v_mov_b32_e32 v46, v6
	v_mov_b32_e32 v47, v6
	v_mov_b32_e32 v48, v6
	v_mov_b32_e32 v49, v6
	v_mov_b32_e32 v34, v6
	v_mov_b32_e32 v35, v6
	v_mov_b32_e32 v36, v6
	v_mov_b32_e32 v37, v6
	v_mov_b32_e32 v62, v6
	v_mov_b32_e32 v63, v6
	v_mov_b32_e32 v64, v6
	v_mov_b32_e32 v65, v6
	v_mov_b32_e32 v50, v6
	v_mov_b32_e32 v51, v6
	v_mov_b32_e32 v52, v6
	v_mov_b32_e32 v53, v6
	v_mov_b32_e32 v70, v6
	v_mov_b32_e32 v71, v6
	v_mov_b32_e32 v72, v6
	v_mov_b32_e32 v73, v6
	v_mov_b32_e32 v74, v6
	v_mov_b32_e32 v75, v6
	v_mov_b32_e32 v76, v6
	v_mov_b32_e32 v77, v6
	v_mov_b32_e32 v86, v6
	v_mov_b32_e32 v87, v6
	v_mov_b32_e32 v88, v6
	v_mov_b32_e32 v89, v6
	v_mov_b32_e32 v90, v6
	v_mov_b32_e32 v91, v6
	v_mov_b32_e32 v92, v6
	v_mov_b32_e32 v93, v6
	v_mov_b32_e32 v102, v6
	v_mov_b32_e32 v103, v6
	v_mov_b32_e32 v104, v6
	v_mov_b32_e32 v105, v6
	v_mov_b32_e32 v106, v6
	v_mov_b32_e32 v107, v6
	v_mov_b32_e32 v108, v6
	v_mov_b32_e32 v109, v6
	v_mov_b32_e32 v118, v6
	v_mov_b32_e32 v119, v6
	v_mov_b32_e32 v120, v6
	v_mov_b32_e32 v121, v6
	v_mov_b32_e32 v122, v6
	v_mov_b32_e32 v123, v6
	v_mov_b32_e32 v124, v6
	v_mov_b32_e32 v125, v6
	v_mov_b32_e32 v78, v6
	v_mov_b32_e32 v79, v6
	v_mov_b32_e32 v80, v6
	v_mov_b32_e32 v81, v6
	v_mov_b32_e32 v66, v6
	v_mov_b32_e32 v67, v6
	v_mov_b32_e32 v68, v6
	v_mov_b32_e32 v69, v6
	v_mov_b32_e32 v94, v6
	v_mov_b32_e32 v95, v6
	v_mov_b32_e32 v96, v6
	v_mov_b32_e32 v97, v6
	v_mov_b32_e32 v82, v6
	v_mov_b32_e32 v83, v6
	v_mov_b32_e32 v84, v6
	v_mov_b32_e32 v85, v6
	v_mov_b32_e32 v110, v6
	v_mov_b32_e32 v111, v6
	v_mov_b32_e32 v112, v6
	v_mov_b32_e32 v113, v6
	v_mov_b32_e32 v98, v6
	v_mov_b32_e32 v99, v6
	v_mov_b32_e32 v100, v6
	v_mov_b32_e32 v101, v6
	v_mov_b32_e32 v126, v6
	v_mov_b32_e32 v127, v6
	v_mov_b32_e32 v128, v6
	v_mov_b32_e32 v129, v6
	v_mov_b32_e32 v114, v6
	v_mov_b32_e32 v115, v6
	v_mov_b32_e32 v116, v6
	v_mov_b32_e32 v117, v6
	.p2align 6

;     __device__ bool next(int i, Unit& u) const { if (i != 0) return false; u.pm = pm; u.pn = pn; return true; }
;     __device__ bool next(int i, Unit& u) const { const int L = i * G + c; if (L >= 256) return false; u.pm = L; u.pn = L >> 6; return true; }
;     __device__ bool next(int i, Unit& u) const { Unit t; if (!so.next(i >> 2, t)) return false; const int b = i & 3; u.pm = b * 64 + t.pm; u.pn = b * 8 + t.pn; return true; }
;     __device__ __forceinline__ bool zero_after(const Unit& u) const { return (u.pm >> 6) == 3; }
; template <bool ALIGN_EPI, bool SP2, class Epi, class Sched>
; __device__ __forceinline__ void gemm_phase(LAS unsigned char* lds, const Gemm g, const Sched& S, const Epi& E) {
;     ...
;         const bool has_next = S.next(ui + 1, nxt);
;         const char* nA = has_next ? (const char*)g.A + (size_t)nxt.pm * tstep : cA; const char* nB = has_next ? (const char*)g.Bt + (size_t)nxt.pn * tstep : cB;
;         for (int t = 0; t < nt; t += 2) {
;             const bool last = (t == nt - 2);
;             const char* a1 = cA + (size_t)(t + 1) * kstep;
;             const char* a2 = last ? nA : cA + (size_t)(t + 2) * kstep; const char* b2 = last ? nB : cB + (size_t)(t + 2) * kstep;
;             const char* a3 = a2 + kstep; const char* b3 = b2 + kstep;
;     ...
;         E(acc, cur, wr, wc, fr, fq);
;         if (!has_next) break;
;         if (E.zero_after(cur))
; #pragma unroll
;         for (int a = 0; a < 2; ++a)
; #pragma unroll
;             for (int b = 0; b < 2; ++b)
; #pragma unroll
;                 for (int m = 0; m < 4; ++m)
; #pragma unroll
;                     for (int n = 0; n < 2; ++n) acc[a][b][m][n] = (f32x4){0.f, 0.f, 0.f, 0.f};
;         cur = nxt; cA = nA; cB = nB; ++ui;
.LBB0_617:
	v_mov_b32_e32 v129, 0
	s_andn2_b64 vcc, exec, s[42:43]
	v_mov_b32_e32 v128, v129
	v_mov_b32_e32 v127, v129
	v_mov_b32_e32 v126, v129
	v_mov_b32_e32 v125, v129
	v_mov_b32_e32 v124, v129
	v_mov_b32_e32 v123, v129
	v_mov_b32_e32 v122, v129
	v_mov_b32_e32 v113, v129
	v_mov_b32_e32 v112, v129
	v_mov_b32_e32 v111, v129
	v_mov_b32_e32 v110, v129
	v_mov_b32_e32 v109, v129
	v_mov_b32_e32 v108, v129
	v_mov_b32_e32 v107, v129
	v_mov_b32_e32 v106, v129
	v_mov_b32_e32 v97, v129
	v_mov_b32_e32 v96, v129
	v_mov_b32_e32 v95, v129
	v_mov_b32_e32 v94, v129
	v_mov_b32_e32 v93, v129
	v_mov_b32_e32 v92, v129
	v_mov_b32_e32 v91, v129
	v_mov_b32_e32 v90, v129
	v_mov_b32_e32 v81, v129
	v_mov_b32_e32 v80, v129
	v_mov_b32_e32 v79, v129
	v_mov_b32_e32 v78, v129
	v_mov_b32_e32 v77, v129
	v_mov_b32_e32 v76, v129
	v_mov_b32_e32 v75, v129
	v_mov_b32_e32 v74, v129
	v_mov_b32_e32 v121, v129
	v_mov_b32_e32 v120, v129
	v_mov_b32_e32 v119, v129
	v_mov_b32_e32 v118, v129
	v_mov_b32_e32 v117, v129
	v_mov_b32_e32 v116, v129
	v_mov_b32_e32 v115, v129
	v_mov_b32_e32 v114, v129
	v_mov_b32_e32 v105, v129
	v_mov_b32_e32 v104, v129
	v_mov_b32_e32 v103, v129
	v_mov_b32_e32 v102, v129
	v_mov_b32_e32 v101, v129
	v_mov_b32_e32 v100, v129
	v_mov_b32_e32 v99, v129
	v_mov_b32_e32 v98, v129
	v_mov_b32_e32 v89, v129
	v_mov_b32_e32 v88, v129
	v_mov_b32_e32 v87, v129
	v_mov_b32_e32 v86, v129
	v_mov_b32_e32 v85, v129
	v_mov_b32_e32 v84, v129
	v_mov_b32_e32 v83, v129
	v_mov_b32_e32 v82, v129
	v_mov_b32_e32 v73, v129
	v_mov_b32_e32 v72, v129
	v_mov_b32_e32 v71, v129
	v_mov_b32_e32 v70, v129
	v_mov_b32_e32 v69, v129
	v_mov_b32_e32 v68, v129
	v_mov_b32_e32 v67, v129
	v_mov_b32_e32 v66, v129
	v_mov_b32_e32 v65, v129
	v_mov_b32_e32 v64, v129
	v_mov_b32_e32 v63, v129
	v_mov_b32_e32 v62, v129
	v_mov_b32_e32 v61, v129
	v_mov_b32_e32 v60, v129
	v_mov_b32_e32 v59, v129
	v_mov_b32_e32 v58, v129
	v_mov_b32_e32 v49, v129
	v_mov_b32_e32 v48, v129
	v_mov_b32_e32 v47, v129
	v_mov_b32_e32 v46, v129
	v_mov_b32_e32 v45, v129
	v_mov_b32_e32 v44, v129
	v_mov_b32_e32 v43, v129
	v_mov_b32_e32 v42, v129
	v_mov_b32_e32 v33, v129
	v_mov_b32_e32 v32, v129
	v_mov_b32_e32 v31, v129
	v_mov_b32_e32 v30, v129
	v_mov_b32_e32 v29, v129
	v_mov_b32_e32 v28, v129
	v_mov_b32_e32 v27, v129
	v_mov_b32_e32 v26, v129
	v_mov_b32_e32 v17, v129
	v_mov_b32_e32 v16, v129
	v_mov_b32_e32 v15, v129
	v_mov_b32_e32 v14, v129
	v_mov_b32_e32 v13, v129
	v_mov_b32_e32 v12, v129
	v_mov_b32_e32 v11, v129
	v_mov_b32_e32 v10, v129
	v_mov_b32_e32 v57, v129
	v_mov_b32_e32 v56, v129
	v_mov_b32_e32 v55, v129
	v_mov_b32_e32 v54, v129
	v_mov_b32_e32 v53, v129
	v_mov_b32_e32 v52, v129
	v_mov_b32_e32 v51, v129
	v_mov_b32_e32 v50, v129
	v_mov_b32_e32 v41, v129
	v_mov_b32_e32 v40, v129
	v_mov_b32_e32 v39, v129
	v_mov_b32_e32 v38, v129
	v_mov_b32_e32 v37, v129
	v_mov_b32_e32 v36, v129
	v_mov_b32_e32 v35, v129
	v_mov_b32_e32 v34, v129
	v_mov_b32_e32 v25, v129
	v_mov_b32_e32 v24, v129
	v_mov_b32_e32 v23, v129
	v_mov_b32_e32 v22, v129
	v_mov_b32_e32 v21, v129
	v_mov_b32_e32 v20, v129
	v_mov_b32_e32 v19, v129
	v_mov_b32_e32 v18, v129
	v_mov_b32_e32 v9, v129
	v_mov_b32_e32 v8, v129
	v_mov_b32_e32 v7, v129
	v_mov_b32_e32 v6, v129
	v_mov_b32_e32 v5, v129
	v_mov_b32_e32 v4, v129
	v_mov_b32_e32 v3, v129
	v_mov_b32_e32 v2, v129
	s_cbranch_vccnz .LBB0_621
	s_add_u32 s86, s86, 0x80
	s_addc_u32 s87, s87, 0
	s_add_u32 s24, s90, 0x100
	v_mov_b32_e32 v2, 0
	s_addc_u32 s71, s91, 0
	s_mov_b32 s88, 0
	.p2align 6

; __device__ __forceinline__ void phase_ln(KP p, int l) {
;     ...
;     for (int row = blockIdx.x * 8 + wid; row < SEQ; row += gridDim.x * 8) {
.LBB0_899:
	v_add_u32_e32 v34, s40, v34
	s_movk_i32 s6, 0x3fff
	v_cmp_lt_i32_e32 vcc, s6, v34
	s_or_b64 s[0:1], vcc, s[0:1]
	s_andn2_b64 exec, exec, s[0:1]
	s_cbranch_execz .LBB0_916
	.p2align 6
